# baseline (speedup 1.0000x reference)
; __device__ __forceinline__ unsigned cvt_pk_bf16(float lo, float hi) { const f32x2 v = {lo, hi}; const bf16v2 r = __builtin_convertvector(v, bf16v2); return __builtin_bit_cast(unsigned, r); }
; __device__ __forceinline__ void convert_tile(LAS float* tile, const float* __restrict__ src, int N, int k0, int n0, bf16_t* __restrict__ dst, int K, int dst_row0) {
;     ...
;     for (int i = 0; i < 2; ++i) { const int idx = tid + 512 * i, k = idx >> 4, n4 = (idx & 15) * 4;
;         const f32x4 v = *(const f32x4*)(src + (size_t)(k0 + k) * N + n0 + n4);
;         tile[k * 65 + n4] = v[0]; tile[k * 65 + n4 + 1] = v[1]; tile[k * 65 + n4 + 2] = v[2]; tile[k * 65 + n4 + 3] = v[3]; }
;     __syncthreads();
;     { const int n = tid >> 3, kc = (tid & 7) * 8; float f[8];
; #pragma unroll
;       for (int j = 0; j < 8; ++j) f[j] = tile[(kc + j) * 65 + n];
;       u32x4 w; w.x = cvt_pk_bf16(f[0], f[1]); w.y = cvt_pk_bf16(f[2], f[3]); w.z = cvt_pk_bf16(f[4], f[5]); w.w = cvt_pk_bf16(f[6], f[7]);
;       *(u32x4*)(dst + (size_t)(dst_row0 + n) * K + k0 + kc) = w; }
; __device__ void convert_mat(LAS float* tile, const float* src, int K, int N, bf16_t* dst, int mode, int rank, int stride) {
;     ...
;     for (int t = rank; t < nt; t += stride) { const int kt = t / nnt, n0 = (t % nnt) * 64;
;         const int drow = mode == 0 ? n0 : (n0 >> 7) * 256 + (n0 & 127) + (mode - 1) * 128;
;         convert_tile(tile, src, N, kt * 64, n0, dst, K, drow); }
.LBB0_379:
	s_mul_hi_i32 s0, s2, 0x2fa0be83
	s_lshr_b32 s1, s0, 31
	s_ashr_i32 s0, s0, 4
	s_add_i32 s0, s0, s1
	s_mul_i32 s1, s0, 0xffffea80
	s_add_i32 s14, s5, s1
	s_mul_i32 s1, s0, 0xffffd500
	s_add_i32 s1, s7, s1
	s_and_b32 s1, s1, 0xffffff00
	s_and_b32 s13, s14, 64
	s_ashr_i32 s15, s14, 31
	s_or_b32 s1, s13, s1
	s_lshl_b32 s0, s0, 6
	v_mov_b32_e32 v10, v226
	s_lshl_b64 s[14:15], s[14:15], 2
	s_add_u32 s14, s3, s14
	v_lshlrev_b32_e32 v0, 4, v10
	s_addc_u32 s15, s4, s15
	v_and_b32_e32 v0, 0xf0, v0
	v_ashrrev_i32_e32 v8, 4, v10
	v_lshl_add_u64 v[6:7], s[14:15], 0, v[0:1]
	v_add_u32_e32 v2, s0, v8
	v_mad_i64_i32 v[2:3], s[14:15], v2, s16, v[6:7]
	global_load_dwordx4 v[2:5], v[2:3], off nt
	v_add_u32_e32 v0, 0, v0
	v_mad_u64_u32 v[8:9], s[14:15], v8, s17, v[0:1]
	s_add_i32 s2, s2, s10
	s_add_i32 s5, s5, s6
	s_add_i32 s7, s7, s12
	v_add_u32_e32 v92, 0x200, v10
	v_ashrrev_i32_e32 v96, 4, v92
	v_add_u32_e32 v92, s0, v96
	v_mad_i64_i32 v[92:93], s[14:15], v92, s16, v[6:7]
	global_load_dwordx4 v[92:95], v[92:93], off nt
	v_mad_u64_u32 v[6:7], s[14:15], v96, s17, v[0:1]
	s_waitcnt vmcnt(1)
	ds_write2_b32 v8, v2, v3 offset1:1
	ds_write2_b32 v8, v4, v5 offset0:2 offset1:3
	v_ashrrev_i32_e32 v0, 3, v10
	s_waitcnt vmcnt(0)
	ds_write2_b32 v6, v92, v93 offset1:1
	ds_write2_b32 v6, v94, v95 offset0:2 offset1:3
	v_lshlrev_b32_e32 v2, 3, v10
	v_and_b32_e32 v10, 56, v2
	v_lshlrev_b32_e32 v2, 2, v0
	v_mul_u32_u24_e32 v3, 0x104, v10
	v_add3_u32 v6, 0, v2, v3
	s_waitcnt lgkmcnt(0)
	s_barrier
	ds_read2_b32 v[2:3], v6 offset1:65
	ds_read2_b32 v[4:5], v6 offset0:130 offset1:195
	v_add_u32_e32 v8, 0x400, v6
	ds_read2_b32 v[6:7], v8 offset0:4 offset1:69
	ds_read2_b32 v[8:9], v8 offset0:134 offset1:199
	s_waitcnt lgkmcnt(3)
	v_cvt_pk_bf16_f32 v2, v2, v3
	s_waitcnt lgkmcnt(2)
	v_cvt_pk_bf16_f32 v3, v4, v5
	s_waitcnt lgkmcnt(1)
	v_cvt_pk_bf16_f32 v4, v6, v7
	v_add_u32_e32 v6, s1, v0
	v_ashrrev_i32_e32 v7, 31, v6
	v_lshlrev_b64 v[6:7], 12, v[6:7]
	v_lshl_add_u64 v[6:7], s[98:99], 0, v[6:7]
	s_ashr_i32 s1, s0, 31
	v_lshl_add_u64 v[6:7], s[0:1], 1, v[6:7]
	v_lshlrev_b32_e32 v0, 1, v10
	s_waitcnt lgkmcnt(0)
	v_cvt_pk_bf16_f32 v5, v8, v9
	v_lshl_add_u64 v[6:7], v[6:7], 0, v[0:1]
	s_cmpk_lt_i32 s2, 0xac0
	global_store_dwordx4 v[6:7], v[2:5], off
	s_barrier
	s_cbranch_scc1 .LBB0_379

; __device__ __forceinline__ unsigned cvt_pk_bf16(float lo, float hi) { const f32x2 v = {lo, hi}; const bf16v2 r = __builtin_convertvector(v, bf16v2); return __builtin_bit_cast(unsigned, r); }
; __device__ __forceinline__ void convert_tile(LAS float* tile, const float* __restrict__ src, int N, int k0, int n0, bf16_t* __restrict__ dst, int K, int dst_row0) {
;     ...
;     for (int i = 0; i < 2; ++i) { const int idx = tid + 512 * i, k = idx >> 4, n4 = (idx & 15) * 4;
;         const f32x4 v = *(const f32x4*)(src + (size_t)(k0 + k) * N + n0 + n4);
;         tile[k * 65 + n4] = v[0]; tile[k * 65 + n4 + 1] = v[1]; tile[k * 65 + n4 + 2] = v[2]; tile[k * 65 + n4 + 3] = v[3]; }
;     __syncthreads();
;     { const int n = tid >> 3, kc = (tid & 7) * 8; float f[8];
; #pragma unroll
;       for (int j = 0; j < 8; ++j) f[j] = tile[(kc + j) * 65 + n];
;       u32x4 w; w.x = cvt_pk_bf16(f[0], f[1]); w.y = cvt_pk_bf16(f[2], f[3]); w.z = cvt_pk_bf16(f[4], f[5]); w.w = cvt_pk_bf16(f[6], f[7]);
;       *(u32x4*)(dst + (size_t)(dst_row0 + n) * K + k0 + kc) = w; }
; __device__ void convert_mat(LAS float* tile, const float* src, int K, int N, bf16_t* dst, int mode, int rank, int stride) {
;     ...
;     for (int t = rank; t < nt; t += stride) { const int kt = t / nnt, n0 = (t % nnt) * 64;
;         const int drow = mode == 0 ? n0 : (n0 >> 7) * 256 + (n0 & 127) + (mode - 1) * 128;
;         convert_tile(tile, src, N, kt * 64, n0, dst, K, drow); }
.LBB0_382:
	s_mul_hi_i32 s0, s2, 0x2fa0be83
	s_lshr_b32 s1, s0, 31
	s_ashr_i32 s0, s0, 4
	s_add_i32 s0, s0, s1
	s_mul_i32 s1, s0, 0xffffea80
	s_add_i32 s14, s5, s1
	s_and_b32 s1, s5, 64
	s_mul_i32 s13, s0, 0x2b00
	s_sub_i32 s1, s1, s13
	s_add_i32 s1, s7, s1
	s_ashr_i32 s15, s14, 31
	s_bitset1_b32 s1, 7
	s_lshl_b32 s0, s0, 6
	v_mov_b32_e32 v10, v226
	s_lshl_b64 s[14:15], s[14:15], 2
	s_add_u32 s14, s3, s14
	v_lshlrev_b32_e32 v0, 4, v10
	s_addc_u32 s15, s4, s15
	v_and_b32_e32 v0, 0xf0, v0
	v_ashrrev_i32_e32 v8, 4, v10
	v_lshl_add_u64 v[6:7], s[14:15], 0, v[0:1]
	v_add_u32_e32 v2, s0, v8
	v_mad_i64_i32 v[2:3], s[14:15], v2, s16, v[6:7]
	global_load_dwordx4 v[2:5], v[2:3], off nt
	v_add_u32_e32 v0, 0, v0
	v_mad_u64_u32 v[8:9], s[14:15], v8, s17, v[0:1]
	s_add_i32 s2, s2, s10
	s_add_i32 s5, s5, s6
	s_add_i32 s7, s7, s12
	v_add_u32_e32 v92, 0x200, v10
	v_ashrrev_i32_e32 v96, 4, v92
	v_add_u32_e32 v92, s0, v96
	v_mad_i64_i32 v[92:93], s[14:15], v92, s16, v[6:7]
	global_load_dwordx4 v[92:95], v[92:93], off nt
	v_mad_u64_u32 v[6:7], s[14:15], v96, s17, v[0:1]
	s_waitcnt vmcnt(1)
	ds_write2_b32 v8, v2, v3 offset1:1
	ds_write2_b32 v8, v4, v5 offset0:2 offset1:3
	v_ashrrev_i32_e32 v0, 3, v10
	s_waitcnt vmcnt(0)
	ds_write2_b32 v6, v92, v93 offset1:1
	ds_write2_b32 v6, v94, v95 offset0:2 offset1:3
	v_lshlrev_b32_e32 v2, 3, v10
	v_and_b32_e32 v10, 56, v2
	v_lshlrev_b32_e32 v2, 2, v0
	v_mul_u32_u24_e32 v3, 0x104, v10
	v_add3_u32 v6, 0, v2, v3
	s_waitcnt lgkmcnt(0)
	s_barrier
	ds_read2_b32 v[2:3], v6 offset1:65
	ds_read2_b32 v[4:5], v6 offset0:130 offset1:195
	v_add_u32_e32 v8, 0x400, v6
	ds_read2_b32 v[6:7], v8 offset0:4 offset1:69
	ds_read2_b32 v[8:9], v8 offset0:134 offset1:199
	s_waitcnt lgkmcnt(3)
	v_cvt_pk_bf16_f32 v2, v2, v3
	s_waitcnt lgkmcnt(2)
	v_cvt_pk_bf16_f32 v3, v4, v5
	s_waitcnt lgkmcnt(1)
	v_cvt_pk_bf16_f32 v4, v6, v7
	v_add_u32_e32 v6, s1, v0
	v_ashrrev_i32_e32 v7, 31, v6
	v_lshlrev_b64 v[6:7], 12, v[6:7]
	v_lshl_add_u64 v[6:7], s[98:99], 0, v[6:7]
	s_ashr_i32 s1, s0, 31
	v_lshl_add_u64 v[6:7], s[0:1], 1, v[6:7]
	v_lshlrev_b32_e32 v0, 1, v10
	s_waitcnt lgkmcnt(0)
	v_cvt_pk_bf16_f32 v5, v8, v9
	v_lshl_add_u64 v[6:7], v[6:7], 0, v[0:1]
	s_cmpk_gt_i32 s2, 0xabf
	global_store_dwordx4 v[6:7], v[2:5], off
	s_barrier
	s_cbranch_scc0 .LBB0_382

; __device__ __forceinline__ unsigned cvt_pk_bf16(float lo, float hi) { const f32x2 v = {lo, hi}; const bf16v2 r = __builtin_convertvector(v, bf16v2); return __builtin_bit_cast(unsigned, r); }
; __device__ __forceinline__ void convert_tile(LAS float* tile, const float* __restrict__ src, int N, int k0, int n0, bf16_t* __restrict__ dst, int K, int dst_row0) {
;     ...
;     for (int i = 0; i < 2; ++i) { const int idx = tid + 512 * i, k = idx >> 4, n4 = (idx & 15) * 4;
;         const f32x4 v = *(const f32x4*)(src + (size_t)(k0 + k) * N + n0 + n4);
;         tile[k * 65 + n4] = v[0]; tile[k * 65 + n4 + 1] = v[1]; tile[k * 65 + n4 + 2] = v[2]; tile[k * 65 + n4 + 3] = v[3]; }
;     __syncthreads();
;     { const int n = tid >> 3, kc = (tid & 7) * 8; float f[8];
; #pragma unroll
;       for (int j = 0; j < 8; ++j) f[j] = tile[(kc + j) * 65 + n];
;       u32x4 w; w.x = cvt_pk_bf16(f[0], f[1]); w.y = cvt_pk_bf16(f[2], f[3]); w.z = cvt_pk_bf16(f[4], f[5]); w.w = cvt_pk_bf16(f[6], f[7]);
;       *(u32x4*)(dst + (size_t)(dst_row0 + n) * K + k0 + kc) = w; }
; __device__ void convert_mat(LAS float* tile, const float* src, int K, int N, bf16_t* dst, int mode, int rank, int stride) {
;     ...
;     for (int t = rank; t < nt; t += stride) { const int kt = t / nnt, n0 = (t % nnt) * 64;
;         const int drow = mode == 0 ? n0 : (n0 >> 7) * 256 + (n0 & 127) + (mode - 1) * 128;
;         convert_tile(tile, src, N, kt * 64, n0, dst, K, drow); }
.LBB0_396:
	s_mul_hi_i32 s0, s2, 0x2fa0be83
	s_lshr_b32 s1, s0, 31
	s_ashr_i32 s0, s0, 4
	s_add_i32 s0, s0, s1
	s_mul_i32 s1, s0, 0xffffea80
	s_add_i32 s14, s5, s1
	s_mul_i32 s1, s0, 0xffffd500
	s_add_i32 s1, s7, s1
	s_and_b32 s1, s1, 0xffffff00
	s_and_b32 s13, s14, 64
	s_ashr_i32 s15, s14, 31
	s_or_b32 s1, s13, s1
	s_lshl_b32 s0, s0, 6
	s_waitcnt vmcnt(0)
	v_mov_b32_e32 v10, v226
	s_lshl_b64 s[14:15], s[14:15], 2
	s_add_u32 s14, s3, s14
	v_lshlrev_b32_e32 v0, 4, v10
	s_addc_u32 s15, s4, s15
	v_and_b32_e32 v0, 0xf0, v0
	v_ashrrev_i32_e32 v8, 4, v10
	v_lshl_add_u64 v[6:7], s[14:15], 0, v[0:1]
	v_add_u32_e32 v2, s0, v8
	v_mad_i64_i32 v[2:3], s[14:15], v2, s16, v[6:7]
	global_load_dwordx4 v[2:5], v[2:3], off nt
	v_add_u32_e32 v0, 0, v0
	v_mad_u64_u32 v[8:9], s[14:15], v8, s17, v[0:1]
	s_add_i32 s2, s2, s10
	s_add_i32 s5, s5, s6
	s_add_i32 s7, s7, s12
	v_add_u32_e32 v92, 0x200, v10
	v_ashrrev_i32_e32 v96, 4, v92
	v_add_u32_e32 v92, s0, v96
	v_mad_i64_i32 v[92:93], s[14:15], v92, s16, v[6:7]
	global_load_dwordx4 v[92:95], v[92:93], off nt
	v_mad_u64_u32 v[6:7], s[14:15], v96, s17, v[0:1]
	s_waitcnt vmcnt(1)
	ds_write2_b32 v8, v2, v3 offset1:1
	ds_write2_b32 v8, v4, v5 offset0:2 offset1:3
	v_ashrrev_i32_e32 v0, 3, v10
	s_waitcnt vmcnt(0)
	ds_write2_b32 v6, v92, v93 offset1:1
	ds_write2_b32 v6, v94, v95 offset0:2 offset1:3
	v_lshlrev_b32_e32 v2, 3, v10
	v_and_b32_e32 v10, 56, v2
	v_lshlrev_b32_e32 v2, 2, v0
	v_mul_u32_u24_e32 v3, 0x104, v10
	v_add3_u32 v6, 0, v2, v3
	s_waitcnt lgkmcnt(0)
	s_barrier
	ds_read2_b32 v[2:3], v6 offset1:65
	ds_read2_b32 v[4:5], v6 offset0:130 offset1:195
	v_add_u32_e32 v8, 0x400, v6
	ds_read2_b32 v[6:7], v8 offset0:4 offset1:69
	ds_read2_b32 v[8:9], v8 offset0:134 offset1:199
	s_waitcnt lgkmcnt(3)
	v_cvt_pk_bf16_f32 v2, v2, v3
	s_waitcnt lgkmcnt(2)
	v_cvt_pk_bf16_f32 v3, v4, v5
	s_waitcnt lgkmcnt(1)
	v_cvt_pk_bf16_f32 v4, v6, v7
	v_add_u32_e32 v6, s1, v0
	v_ashrrev_i32_e32 v7, 31, v6
	v_lshlrev_b64 v[6:7], 12, v[6:7]
	v_lshl_add_u64 v[6:7], s[98:99], 0, v[6:7]
	s_ashr_i32 s1, s0, 31
	v_lshl_add_u64 v[6:7], s[0:1], 1, v[6:7]
	v_lshlrev_b32_e32 v0, 1, v10
	s_waitcnt lgkmcnt(0)
	v_cvt_pk_bf16_f32 v5, v8, v9
	v_lshl_add_u64 v[6:7], v[6:7], 0, v[0:1]
	s_cmpk_lt_i32 s2, 0xac0
	global_store_dwordx4 v[6:7], v[2:5], off
	s_barrier
	s_cbranch_scc1 .LBB0_396

; __device__ __forceinline__ unsigned cvt_pk_bf16(float lo, float hi) { const f32x2 v = {lo, hi}; const bf16v2 r = __builtin_convertvector(v, bf16v2); return __builtin_bit_cast(unsigned, r); }
; __device__ __forceinline__ void convert_tile(LAS float* tile, const float* __restrict__ src, int N, int k0, int n0, bf16_t* __restrict__ dst, int K, int dst_row0) {
;     ...
;     for (int i = 0; i < 2; ++i) { const int idx = tid + 512 * i, k = idx >> 4, n4 = (idx & 15) * 4;
;         const f32x4 v = *(const f32x4*)(src + (size_t)(k0 + k) * N + n0 + n4);
;         tile[k * 65 + n4] = v[0]; tile[k * 65 + n4 + 1] = v[1]; tile[k * 65 + n4 + 2] = v[2]; tile[k * 65 + n4 + 3] = v[3]; }
;     __syncthreads();
;     { const int n = tid >> 3, kc = (tid & 7) * 8; float f[8];
; #pragma unroll
;       for (int j = 0; j < 8; ++j) f[j] = tile[(kc + j) * 65 + n];
;       u32x4 w; w.x = cvt_pk_bf16(f[0], f[1]); w.y = cvt_pk_bf16(f[2], f[3]); w.z = cvt_pk_bf16(f[4], f[5]); w.w = cvt_pk_bf16(f[6], f[7]);
;       *(u32x4*)(dst + (size_t)(dst_row0 + n) * K + k0 + kc) = w; }
; __device__ void convert_mat(LAS float* tile, const float* src, int K, int N, bf16_t* dst, int mode, int rank, int stride) {
;     ...
;     for (int t = rank; t < nt; t += stride) { const int kt = t / nnt, n0 = (t % nnt) * 64;
;         const int drow = mode == 0 ? n0 : (n0 >> 7) * 256 + (n0 & 127) + (mode - 1) * 128;
;         convert_tile(tile, src, N, kt * 64, n0, dst, K, drow); }
.LBB0_399:
	s_mul_hi_i32 s0, s2, 0x2fa0be83
	s_lshr_b32 s1, s0, 31
	s_ashr_i32 s0, s0, 4
	s_add_i32 s0, s0, s1
	s_mul_i32 s1, s0, 0xffffea80
	s_add_i32 s14, s5, s1
	s_and_b32 s1, s5, 64
	s_mul_i32 s13, s0, 0x2b00
	s_sub_i32 s1, s1, s13
	s_add_i32 s1, s7, s1
	s_ashr_i32 s15, s14, 31
	s_bitset1_b32 s1, 7
	s_lshl_b32 s0, s0, 6
	s_waitcnt vmcnt(0)
	v_mov_b32_e32 v10, v226
	s_lshl_b64 s[14:15], s[14:15], 2
	s_add_u32 s14, s3, s14
	v_lshlrev_b32_e32 v0, 4, v10
	s_addc_u32 s15, s4, s15
	v_and_b32_e32 v0, 0xf0, v0
	v_ashrrev_i32_e32 v8, 4, v10
	v_lshl_add_u64 v[6:7], s[14:15], 0, v[0:1]
	v_add_u32_e32 v2, s0, v8
	v_mad_i64_i32 v[2:3], s[14:15], v2, s16, v[6:7]
	global_load_dwordx4 v[2:5], v[2:3], off nt
	v_add_u32_e32 v0, 0, v0
	v_mad_u64_u32 v[8:9], s[14:15], v8, s17, v[0:1]
	s_add_i32 s2, s2, s10
	s_add_i32 s5, s5, s6
	s_add_i32 s7, s7, s12
	v_add_u32_e32 v92, 0x200, v10
	v_ashrrev_i32_e32 v96, 4, v92
	v_add_u32_e32 v92, s0, v96
	v_mad_i64_i32 v[92:93], s[14:15], v92, s16, v[6:7]
	global_load_dwordx4 v[92:95], v[92:93], off nt
	v_mad_u64_u32 v[6:7], s[14:15], v96, s17, v[0:1]
	s_waitcnt vmcnt(1)
	ds_write2_b32 v8, v2, v3 offset1:1
	ds_write2_b32 v8, v4, v5 offset0:2 offset1:3
	v_ashrrev_i32_e32 v0, 3, v10
	s_waitcnt vmcnt(0)
	ds_write2_b32 v6, v92, v93 offset1:1
	ds_write2_b32 v6, v94, v95 offset0:2 offset1:3
	v_lshlrev_b32_e32 v2, 3, v10
	v_and_b32_e32 v10, 56, v2
	v_lshlrev_b32_e32 v2, 2, v0
	v_mul_u32_u24_e32 v3, 0x104, v10
	v_add3_u32 v6, 0, v2, v3
	s_waitcnt lgkmcnt(0)
	s_barrier
	ds_read2_b32 v[2:3], v6 offset1:65
	ds_read2_b32 v[4:5], v6 offset0:130 offset1:195
	v_add_u32_e32 v8, 0x400, v6
	ds_read2_b32 v[6:7], v8 offset0:4 offset1:69
	ds_read2_b32 v[8:9], v8 offset0:134 offset1:199
	s_waitcnt lgkmcnt(3)
	v_cvt_pk_bf16_f32 v2, v2, v3
	s_waitcnt lgkmcnt(2)
	v_cvt_pk_bf16_f32 v3, v4, v5
	s_waitcnt lgkmcnt(1)
	v_cvt_pk_bf16_f32 v4, v6, v7
	v_add_u32_e32 v6, s1, v0
	v_ashrrev_i32_e32 v7, 31, v6
	v_lshlrev_b64 v[6:7], 12, v[6:7]
	v_lshl_add_u64 v[6:7], s[98:99], 0, v[6:7]
	s_ashr_i32 s1, s0, 31
	v_lshl_add_u64 v[6:7], s[0:1], 1, v[6:7]
	v_lshlrev_b32_e32 v0, 1, v10
	s_waitcnt lgkmcnt(0)
	v_cvt_pk_bf16_f32 v5, v8, v9
	v_lshl_add_u64 v[6:7], v[6:7], 0, v[0:1]
	s_cmpk_gt_i32 s2, 0xabf
	global_store_dwordx4 v[6:7], v[2:5], off
	s_barrier
	s_cbranch_scc0 .LBB0_399

; __device__ __forceinline__ unsigned cvt_pk_bf16(float lo, float hi) { const f32x2 v = {lo, hi}; const bf16v2 r = __builtin_convertvector(v, bf16v2); return __builtin_bit_cast(unsigned, r); }
; __device__ __forceinline__ void convert_tile(LAS float* tile, const float* __restrict__ src, int N, int k0, int n0, bf16_t* __restrict__ dst, int K, int dst_row0) {
;     ...
;     for (int i = 0; i < 2; ++i) { const int idx = tid + 512 * i, k = idx >> 4, n4 = (idx & 15) * 4;
;         const f32x4 v = *(const f32x4*)(src + (size_t)(k0 + k) * N + n0 + n4);
;         tile[k * 65 + n4] = v[0]; tile[k * 65 + n4 + 1] = v[1]; tile[k * 65 + n4 + 2] = v[2]; tile[k * 65 + n4 + 3] = v[3]; }
;     __syncthreads();
;     { const int n = tid >> 3, kc = (tid & 7) * 8; float f[8];
; #pragma unroll
;       for (int j = 0; j < 8; ++j) f[j] = tile[(kc + j) * 65 + n];
;       u32x4 w; w.x = cvt_pk_bf16(f[0], f[1]); w.y = cvt_pk_bf16(f[2], f[3]); w.z = cvt_pk_bf16(f[4], f[5]); w.w = cvt_pk_bf16(f[6], f[7]);
;       *(u32x4*)(dst + (size_t)(dst_row0 + n) * K + k0 + kc) = w; }
; __device__ void convert_mat(LAS float* tile, const float* src, int K, int N, bf16_t* dst, int mode, int rank, int stride) {
;     ...
;     for (int t = rank; t < nt; t += stride) { const int kt = t / nnt, n0 = (t % nnt) * 64;
;         const int drow = mode == 0 ? n0 : (n0 >> 7) * 256 + (n0 & 127) + (mode - 1) * 128;
;         convert_tile(tile, src, N, kt * 64, n0, dst, K, drow); }
.LBB0_684:
	s_ashr_i32 s0, s12, 31
	s_lshr_b32 s0, s0, 27
	s_add_i32 s0, s12, s0
	s_ashr_i32 s0, s0, 5
	s_lshl_b32 s1, s0, 11
	s_sub_i32 s14, s6, s1
	v_mov_b32_e32 v10, v226
	s_ashr_i32 s15, s14, 31
	s_lshl_b32 s0, s0, 6
	s_lshl_b64 s[14:15], s[14:15], 2
	v_ashrrev_i32_e32 v8, 4, v10
	s_add_u32 s14, s4, s14
	v_lshlrev_b32_e32 v0, 4, v10
	v_add_u32_e32 v2, s0, v8
	s_addc_u32 s15, s5, s15
	v_and_b32_e32 v0, 0xf0, v0
	v_ashrrev_i32_e32 v3, 31, v2
	v_lshl_add_u64 v[6:7], s[14:15], 0, v[0:1]
	v_lshlrev_b64 v[2:3], 13, v[2:3]
	v_lshl_add_u64 v[2:3], v[6:7], 0, v[2:3]
	global_load_dwordx4 v[2:5], v[2:3], off nt
	v_add_u32_e32 v0, 0, v0
	v_mad_u64_u32 v[8:9], s[14:15], v8, s18, v[0:1]
	s_add_i32 s12, s12, s3
	v_add_u32_e32 v92, 0x200, v10
	v_ashrrev_i32_e32 v96, 4, v92
	v_add_u32_e32 v92, s0, v96
	v_ashrrev_i32_e32 v93, 31, v92
	v_lshlrev_b64 v[92:93], 13, v[92:93]
	v_lshl_add_u64 v[92:93], v[6:7], 0, v[92:93]
	global_load_dwordx4 v[92:95], v[92:93], off nt
	v_mad_u64_u32 v[6:7], s[14:15], v96, s18, v[0:1]
	s_waitcnt vmcnt(1)
	ds_write2_b32 v8, v2, v3 offset1:1
	ds_write2_b32 v8, v4, v5 offset0:2 offset1:3
	v_ashrrev_i32_e32 v0, 3, v10
	s_waitcnt vmcnt(0)
	ds_write2_b32 v6, v92, v93 offset1:1
	ds_write2_b32 v6, v94, v95 offset0:2 offset1:3
	v_lshlrev_b32_e32 v2, 3, v10
	v_and_b32_e32 v10, 56, v2
	v_lshlrev_b32_e32 v2, 2, v0
	v_mul_u32_u24_e32 v3, 0x104, v10
	v_add3_u32 v6, 0, v2, v3
	s_waitcnt lgkmcnt(0)
	s_barrier
	ds_read2_b32 v[2:3], v6 offset1:65
	ds_read2_b32 v[4:5], v6 offset0:130 offset1:195
	v_add_u32_e32 v8, 0x400, v6
	ds_read2_b32 v[6:7], v8 offset0:4 offset1:69
	ds_read2_b32 v[8:9], v8 offset0:134 offset1:199
	v_subrev_u32_e32 v0, s1, v0
	s_waitcnt lgkmcnt(3)
	v_cvt_pk_bf16_f32 v2, v2, v3
	s_waitcnt lgkmcnt(2)
	v_cvt_pk_bf16_f32 v3, v4, v5
	s_waitcnt lgkmcnt(1)
	v_cvt_pk_bf16_f32 v4, v6, v7
	v_add_u32_e32 v0, s6, v0
	v_mov_b64_e32 v[6:7], s[86:87]
	v_mad_i64_i32 v[6:7], s[14:15], v0, s13, v[6:7]
	s_ashr_i32 s1, s0, 31
	v_lshl_add_u64 v[6:7], s[0:1], 1, v[6:7]
	v_lshlrev_b32_e32 v0, 1, v10
	s_add_i32 s6, s6, s7
	s_waitcnt lgkmcnt(0)
	v_cvt_pk_bf16_f32 v5, v8, v9
	v_lshl_add_u64 v[6:7], v[6:7], 0, v[0:1]
	s_cmpk_gt_i32 s12, 0xabf
	global_store_dwordx4 v[6:7], v[2:5], off
	s_barrier
	s_cbranch_scc0 .LBB0_684

; __device__ __forceinline__ unsigned cvt_pk_bf16(float lo, float hi) { const f32x2 v = {lo, hi}; const bf16v2 r = __builtin_convertvector(v, bf16v2); return __builtin_bit_cast(unsigned, r); }
; __device__ __forceinline__ void convert_tile(LAS float* tile, const float* __restrict__ src, int N, int k0, int n0, bf16_t* __restrict__ dst, int K, int dst_row0) {
;     ...
;     for (int i = 0; i < 2; ++i) { const int idx = tid + 512 * i, k = idx >> 4, n4 = (idx & 15) * 4;
;         const f32x4 v = *(const f32x4*)(src + (size_t)(k0 + k) * N + n0 + n4);
;         tile[k * 65 + n4] = v[0]; tile[k * 65 + n4 + 1] = v[1]; tile[k * 65 + n4 + 2] = v[2]; tile[k * 65 + n4 + 3] = v[3]; }
;     __syncthreads();
;     { const int n = tid >> 3, kc = (tid & 7) * 8; float f[8];
; #pragma unroll
;       for (int j = 0; j < 8; ++j) f[j] = tile[(kc + j) * 65 + n];
;       u32x4 w; w.x = cvt_pk_bf16(f[0], f[1]); w.y = cvt_pk_bf16(f[2], f[3]); w.z = cvt_pk_bf16(f[4], f[5]); w.w = cvt_pk_bf16(f[6], f[7]);
;       *(u32x4*)(dst + (size_t)(dst_row0 + n) * K + k0 + kc) = w; }
; __device__ void convert_mat(LAS float* tile, const float* src, int K, int N, bf16_t* dst, int mode, int rank, int stride) {
;     ...
;     for (int t = rank; t < nt; t += stride) { const int kt = t / nnt, n0 = (t % nnt) * 64;
;         const int drow = mode == 0 ? n0 : (n0 >> 7) * 256 + (n0 & 127) + (mode - 1) * 128;
;         convert_tile(tile, src, N, kt * 64, n0, dst, K, drow); }
.LBB0_689:
	s_ashr_i32 s0, s12, 31
	s_lshr_b32 s0, s0, 27
	s_add_i32 s0, s12, s0
	s_ashr_i32 s0, s0, 5
	s_lshl_b32 s1, s0, 11
	s_sub_i32 s14, s6, s1
	v_mov_b32_e32 v10, v226
	s_ashr_i32 s15, s14, 31
	s_lshl_b32 s0, s0, 6
	s_lshl_b64 s[14:15], s[14:15], 2
	v_ashrrev_i32_e32 v8, 4, v10
	s_add_u32 s14, s4, s14
	v_lshlrev_b32_e32 v0, 4, v10
	v_add_u32_e32 v2, s0, v8
	s_addc_u32 s15, s5, s15
	v_and_b32_e32 v0, 0xf0, v0
	v_ashrrev_i32_e32 v3, 31, v2
	v_lshl_add_u64 v[6:7], s[14:15], 0, v[0:1]
	v_lshlrev_b64 v[2:3], 13, v[2:3]
	v_lshl_add_u64 v[2:3], v[6:7], 0, v[2:3]
	global_load_dwordx4 v[2:5], v[2:3], off nt
	v_add_u32_e32 v0, 0, v0
	v_mad_u64_u32 v[8:9], s[14:15], v8, s18, v[0:1]
	s_add_i32 s12, s12, s3
	v_add_u32_e32 v92, 0x200, v10
	v_ashrrev_i32_e32 v96, 4, v92
	v_add_u32_e32 v92, s0, v96
	v_ashrrev_i32_e32 v93, 31, v92
	v_lshlrev_b64 v[92:93], 13, v[92:93]
	v_lshl_add_u64 v[92:93], v[6:7], 0, v[92:93]
	global_load_dwordx4 v[92:95], v[92:93], off nt
	v_mad_u64_u32 v[6:7], s[14:15], v96, s18, v[0:1]
	s_waitcnt vmcnt(1)
	ds_write2_b32 v8, v2, v3 offset1:1
	ds_write2_b32 v8, v4, v5 offset0:2 offset1:3
	v_ashrrev_i32_e32 v0, 3, v10
	s_waitcnt vmcnt(0)
	ds_write2_b32 v6, v92, v93 offset1:1
	ds_write2_b32 v6, v94, v95 offset0:2 offset1:3
	v_lshlrev_b32_e32 v2, 3, v10
	v_and_b32_e32 v10, 56, v2
	v_lshlrev_b32_e32 v2, 2, v0
	v_mul_u32_u24_e32 v3, 0x104, v10
	v_add3_u32 v6, 0, v2, v3
	s_waitcnt lgkmcnt(0)
	s_barrier
	ds_read2_b32 v[2:3], v6 offset1:65
	ds_read2_b32 v[4:5], v6 offset0:130 offset1:195
	v_add_u32_e32 v8, 0x400, v6
	ds_read2_b32 v[6:7], v8 offset0:4 offset1:69
	ds_read2_b32 v[8:9], v8 offset0:134 offset1:199
	v_subrev_u32_e32 v0, s1, v0
	s_waitcnt lgkmcnt(3)
	v_cvt_pk_bf16_f32 v2, v2, v3
	s_waitcnt lgkmcnt(2)
	v_cvt_pk_bf16_f32 v3, v4, v5
	s_waitcnt lgkmcnt(1)
	v_cvt_pk_bf16_f32 v4, v6, v7
	v_add_u32_e32 v6, s6, v0
	v_ashrrev_i32_e32 v7, 31, v6
	v_lshlrev_b64 v[6:7], 12, v[6:7]
	v_lshl_add_u64 v[6:7], s[16:17], 0, v[6:7]
	s_ashr_i32 s1, s0, 31
	v_lshl_add_u64 v[6:7], s[0:1], 1, v[6:7]
	v_lshlrev_b32_e32 v0, 1, v10
	s_add_i32 s6, s6, s7
	s_waitcnt lgkmcnt(0)
	v_cvt_pk_bf16_f32 v5, v8, v9
	v_lshl_add_u64 v[6:7], v[6:7], 0, v[0:1]
	s_cmpk_gt_i32 s12, 0x3ff
	global_store_dwordx4 v[6:7], v[2:5], off
	s_barrier
	s_cbranch_scc0 .LBB0_689

; __device__ __forceinline__ unsigned cvt_pk_bf16(float lo, float hi) { const f32x2 v = {lo, hi}; const bf16v2 r = __builtin_convertvector(v, bf16v2); return __builtin_bit_cast(unsigned, r); }
; __device__ __forceinline__ void convert_tile(LAS float* tile, const float* __restrict__ src, int N, int k0, int n0, bf16_t* __restrict__ dst, int K, int dst_row0) {
;     ...
;     for (int i = 0; i < 2; ++i) { const int idx = tid + 512 * i, k = idx >> 4, n4 = (idx & 15) * 4;
;         const f32x4 v = *(const f32x4*)(src + (size_t)(k0 + k) * N + n0 + n4);
;         tile[k * 65 + n4] = v[0]; tile[k * 65 + n4 + 1] = v[1]; tile[k * 65 + n4 + 2] = v[2]; tile[k * 65 + n4 + 3] = v[3]; }
;     __syncthreads();
;     { const int n = tid >> 3, kc = (tid & 7) * 8; float f[8];
; #pragma unroll
;       for (int j = 0; j < 8; ++j) f[j] = tile[(kc + j) * 65 + n];
;       u32x4 w; w.x = cvt_pk_bf16(f[0], f[1]); w.y = cvt_pk_bf16(f[2], f[3]); w.z = cvt_pk_bf16(f[4], f[5]); w.w = cvt_pk_bf16(f[6], f[7]);
;       *(u32x4*)(dst + (size_t)(dst_row0 + n) * K + k0 + kc) = w; }
; __device__ void convert_mat(LAS float* tile, const float* src, int K, int N, bf16_t* dst, int mode, int rank, int stride) {
;     ...
;     for (int t = rank; t < nt; t += stride) { const int kt = t / nnt, n0 = (t % nnt) * 64;
;         const int drow = mode == 0 ? n0 : (n0 >> 7) * 256 + (n0 & 127) + (mode - 1) * 128;
;         convert_tile(tile, src, N, kt * 64, n0, dst, K, drow); }
.LBB0_694:
	s_ashr_i32 s0, s12, 31
	s_lshr_b32 s0, s0, 27
	s_add_i32 s0, s12, s0
	s_ashr_i32 s0, s0, 5
	s_lshl_b32 s1, s0, 11
	s_sub_i32 s14, s6, s1
	v_mov_b32_e32 v10, v226
	s_ashr_i32 s15, s14, 31
	s_lshl_b32 s0, s0, 6
	s_lshl_b64 s[14:15], s[14:15], 2
	v_ashrrev_i32_e32 v8, 4, v10
	s_add_u32 s14, s4, s14
	v_lshlrev_b32_e32 v0, 4, v10
	v_add_u32_e32 v2, s0, v8
	s_addc_u32 s15, s5, s15
	v_and_b32_e32 v0, 0xf0, v0
	v_ashrrev_i32_e32 v3, 31, v2
	v_lshl_add_u64 v[6:7], s[14:15], 0, v[0:1]
	v_lshlrev_b64 v[2:3], 13, v[2:3]
	v_lshl_add_u64 v[2:3], v[6:7], 0, v[2:3]
	global_load_dwordx4 v[2:5], v[2:3], off nt
	v_add_u32_e32 v0, 0, v0
	v_mad_u64_u32 v[8:9], s[14:15], v8, s18, v[0:1]
	s_add_i32 s12, s12, s3
	v_add_u32_e32 v92, 0x200, v10
	v_ashrrev_i32_e32 v96, 4, v92
	v_add_u32_e32 v92, s0, v96
	v_ashrrev_i32_e32 v93, 31, v92
	v_lshlrev_b64 v[92:93], 13, v[92:93]
	v_lshl_add_u64 v[92:93], v[6:7], 0, v[92:93]
	global_load_dwordx4 v[92:95], v[92:93], off nt
	v_mad_u64_u32 v[6:7], s[14:15], v96, s18, v[0:1]
	s_waitcnt vmcnt(1)
	ds_write2_b32 v8, v2, v3 offset1:1
	ds_write2_b32 v8, v4, v5 offset0:2 offset1:3
	v_ashrrev_i32_e32 v0, 3, v10
	s_waitcnt vmcnt(0)
	ds_write2_b32 v6, v92, v93 offset1:1
	ds_write2_b32 v6, v94, v95 offset0:2 offset1:3
	v_lshlrev_b32_e32 v2, 3, v10
	v_and_b32_e32 v10, 56, v2
	v_lshlrev_b32_e32 v2, 2, v0
	v_mul_u32_u24_e32 v3, 0x104, v10
	v_add3_u32 v6, 0, v2, v3
	s_waitcnt lgkmcnt(0)
	s_barrier
	ds_read2_b32 v[2:3], v6 offset1:65
	ds_read2_b32 v[4:5], v6 offset0:130 offset1:195
	v_add_u32_e32 v8, 0x400, v6
	ds_read2_b32 v[6:7], v8 offset0:4 offset1:69
	ds_read2_b32 v[8:9], v8 offset0:134 offset1:199
	v_subrev_u32_e32 v0, s1, v0
	s_waitcnt lgkmcnt(3)
	v_cvt_pk_bf16_f32 v2, v2, v3
	s_waitcnt lgkmcnt(2)
	v_cvt_pk_bf16_f32 v3, v4, v5
	s_waitcnt lgkmcnt(1)
	v_cvt_pk_bf16_f32 v4, v6, v7
	v_add_u32_e32 v0, s6, v0
	v_mov_b64_e32 v[6:7], s[86:87]
	v_mad_i64_i32 v[6:7], s[14:15], v0, s13, v[6:7]
	s_ashr_i32 s1, s0, 31
	v_lshl_add_u64 v[6:7], s[0:1], 1, v[6:7]
	v_lshlrev_b32_e32 v0, 1, v10
	s_add_i32 s6, s6, s7
	s_waitcnt lgkmcnt(0)
	v_cvt_pk_bf16_f32 v5, v8, v9
	v_lshl_add_u64 v[6:7], v[6:7], 0, v[0:1]
	s_cmpk_lt_i32 s12, 0xac0
	global_store_dwordx4 v[6:7], v[2:5], off
	s_barrier
	s_cbranch_scc1 .LBB0_694

; __device__ __forceinline__ unsigned cvt_pk_bf16(float lo, float hi) { const f32x2 v = {lo, hi}; const bf16v2 r = __builtin_convertvector(v, bf16v2); return __builtin_bit_cast(unsigned, r); }
; __device__ __forceinline__ void convert_tile(LAS float* tile, const float* __restrict__ src, int N, int k0, int n0, bf16_t* __restrict__ dst, int K, int dst_row0) {
;     ...
;     for (int i = 0; i < 2; ++i) { const int idx = tid + 512 * i, k = idx >> 4, n4 = (idx & 15) * 4;
;         const f32x4 v = *(const f32x4*)(src + (size_t)(k0 + k) * N + n0 + n4);
;         tile[k * 65 + n4] = v[0]; tile[k * 65 + n4 + 1] = v[1]; tile[k * 65 + n4 + 2] = v[2]; tile[k * 65 + n4 + 3] = v[3]; }
;     __syncthreads();
;     { const int n = tid >> 3, kc = (tid & 7) * 8; float f[8];
; #pragma unroll
;       for (int j = 0; j < 8; ++j) f[j] = tile[(kc + j) * 65 + n];
;       u32x4 w; w.x = cvt_pk_bf16(f[0], f[1]); w.y = cvt_pk_bf16(f[2], f[3]); w.z = cvt_pk_bf16(f[4], f[5]); w.w = cvt_pk_bf16(f[6], f[7]);
;       *(u32x4*)(dst + (size_t)(dst_row0 + n) * K + k0 + kc) = w; }
; __device__ void convert_mat(LAS float* tile, const float* src, int K, int N, bf16_t* dst, int mode, int rank, int stride) {
;     ...
;     for (int t = rank; t < nt; t += stride) { const int kt = t / nnt, n0 = (t % nnt) * 64;
;         const int drow = mode == 0 ? n0 : (n0 >> 7) * 256 + (n0 & 127) + (mode - 1) * 128;
;         convert_tile(tile, src, N, kt * 64, n0, dst, K, drow); }
.LBB0_697:
	s_mul_hi_i32 s0, s2, 0x92492493
	s_add_i32 s0, s0, s2
	s_lshr_b32 s1, s0, 31
	s_ashr_i32 s0, s0, 6
	s_add_i32 s1, s0, s1
	s_mul_i32 s0, s1, 0xffffe400
	s_add_i32 s12, s6, s0
	s_ashr_i32 s13, s12, 31
	s_lshl_b32 s0, s1, 6
	v_mov_b32_e32 v10, v226
	s_lshl_b64 s[12:13], s[12:13], 2
	s_add_u32 s12, s4, s12
	v_lshlrev_b32_e32 v0, 4, v10
	s_addc_u32 s13, s5, s13
	v_and_b32_e32 v0, 0xf0, v0
	v_ashrrev_i32_e32 v8, 4, v10
	v_lshl_add_u64 v[6:7], s[12:13], 0, v[0:1]
	v_add_u32_e32 v2, s0, v8
	v_mad_i64_i32 v[2:3], s[12:13], v2, s20, v[6:7]
	global_load_dwordx4 v[2:5], v[2:3], off nt
	v_add_u32_e32 v0, 0, v0
	v_mad_u64_u32 v[8:9], s[12:13], v8, s18, v[0:1]
	s_mulk_i32 s1, 0x1c00
	s_add_i32 s2, s2, s3
	v_add_u32_e32 v92, 0x200, v10
	v_ashrrev_i32_e32 v96, 4, v92
	v_add_u32_e32 v92, s0, v96
	v_mad_i64_i32 v[92:93], s[12:13], v92, s20, v[6:7]
	global_load_dwordx4 v[92:95], v[92:93], off nt
	v_mad_u64_u32 v[6:7], s[12:13], v96, s18, v[0:1]
	s_waitcnt vmcnt(1)
	ds_write2_b32 v8, v2, v3 offset1:1
	ds_write2_b32 v8, v4, v5 offset0:2 offset1:3
	v_ashrrev_i32_e32 v0, 3, v10
	s_waitcnt vmcnt(0)
	ds_write2_b32 v6, v92, v93 offset1:1
	ds_write2_b32 v6, v94, v95 offset0:2 offset1:3
	v_lshlrev_b32_e32 v2, 3, v10
	v_and_b32_e32 v10, 56, v2
	v_lshlrev_b32_e32 v2, 2, v0
	v_mul_u32_u24_e32 v3, 0x104, v10
	v_add3_u32 v6, 0, v2, v3
	s_waitcnt lgkmcnt(0)
	s_barrier
	ds_read2_b32 v[2:3], v6 offset1:65
	ds_read2_b32 v[4:5], v6 offset0:130 offset1:195
	v_add_u32_e32 v8, 0x400, v6
	ds_read2_b32 v[6:7], v8 offset0:4 offset1:69
	ds_read2_b32 v[8:9], v8 offset0:134 offset1:199
	v_subrev_u32_e32 v0, s1, v0
	s_waitcnt lgkmcnt(3)
	v_cvt_pk_bf16_f32 v2, v2, v3
	s_waitcnt lgkmcnt(2)
	v_cvt_pk_bf16_f32 v3, v4, v5
	s_waitcnt lgkmcnt(1)
	v_cvt_pk_bf16_f32 v4, v6, v7
	v_add_u32_e32 v6, s6, v0
	v_ashrrev_i32_e32 v7, 31, v6
	v_lshlrev_b64 v[6:7], 12, v[6:7]
	v_lshl_add_u64 v[6:7], s[88:89], 0, v[6:7]
	s_ashr_i32 s1, s0, 31
	v_lshl_add_u64 v[6:7], s[0:1], 1, v[6:7]
	v_lshlrev_b32_e32 v0, 1, v10
	s_add_i32 s6, s6, s7
	s_waitcnt lgkmcnt(0)
	v_cvt_pk_bf16_f32 v5, v8, v9
	v_lshl_add_u64 v[6:7], v[6:7], 0, v[0:1]
	s_cmpk_gt_i32 s2, 0xdff
	global_store_dwordx4 v[6:7], v[2:5], off
	s_barrier
	s_cbranch_scc0 .LBB0_697
